# wconv_tile loops: the two tile loads issued together (second load hoisted behind the first, vmcnt(1)/vmcnt(0)) in 11 serialized instances
# speedup vs baseline: 1.0083x; 1.0083x over previous
.LBB0_317:
	s_mul_hi_i32 s1, s0, 0x2aaaaaab
	s_lshr_b32 s4, s1, 31
	s_ashr_i32 s1, s1, 4
	s_add_i32 s1, s1, s4
	s_mul_i32 s4, s1, 0x60
	s_sub_i32 s4, s0, s4
	s_lshl_b32 s10, s4, 6
	s_ashr_i32 s11, s10, 31
	v_mov_b32_e32 v8, v192
	s_lshl_b32 s8, s1, 6
	s_lshl_b64 s[4:5], s[10:11], 2
	s_add_u32 s4, s52, s4
	v_lshlrev_b32_e32 v0, 4, v8
	v_ashrrev_i32_e32 v9, 4, v8
	s_addc_u32 s5, s53, s5
	v_and_b32_e32 v4, 0xf0, v0
	v_mov_b32_e32 v5, v112
	v_lshl_add_u64 v[6:7], s[4:5], 0, v[4:5]
	v_add_u32_e32 v5, s8, v9
	v_mad_i64_i32 v[0:1], s[4:5], v5, s75, v[6:7]
	global_load_dwordx4 v[0:3], v[0:1], off
	v_add_u32_e32 v12, 32, v5
	v_mad_i64_i32 v[12:13], s[4:5], v12, s75, v[6:7]
	global_load_dwordx4 v[14:17], v[12:13], off
	v_mul_lo_u32 v9, v9, s14
	v_add3_u32 v4, 0, v4, v9
	s_ashr_i32 s9, s8, 31
	s_waitcnt vmcnt(1)
	ds_write2_b32 v4, v0, v1 offset1:1
	ds_write2_b32 v4, v2, v3 offset0:2 offset1:3
	v_add_u32_e32 v5, 0x2080, v4
	v_ashrrev_i32_e32 v6, 3, v8
	s_waitcnt vmcnt(0)
	ds_write2_b32 v5, v14, v15 offset1:1
	v_add_u32_e32 v0, 0x2088, v4
	ds_write2_b32 v0, v16, v17 offset1:1
	v_lshlrev_b32_e32 v0, 3, v8
	v_and_b32_e32 v7, 56, v0
	v_mul_u32_u24_e32 v0, 0x104, v7
	v_lshlrev_b32_e32 v1, 2, v6
	v_add3_u32 v4, 0, v0, v1
	s_waitcnt lgkmcnt(0)
	s_barrier
	ds_read2_b32 v[0:1], v4 offset1:65
	ds_read2_b32 v[2:3], v4 offset0:130 offset1:195
	v_add_u32_e32 v4, 0x400, v4
	s_waitcnt lgkmcnt(1)
	v_cvt_pk_bf16_f32 v0, v0, v1
	s_waitcnt lgkmcnt(0)
	v_cvt_pk_bf16_f32 v1, v2, v3
	ds_read2_b32 v[2:3], v4 offset0:4 offset1:69
	ds_read2_b32 v[4:5], v4 offset0:134 offset1:199
	s_waitcnt lgkmcnt(1)
	v_cvt_pk_bf16_f32 v2, v2, v3
	s_waitcnt lgkmcnt(0)
	v_cvt_pk_bf16_f32 v3, v4, v5
	v_add_u32_e32 v4, s10, v6
	v_ashrrev_i32_e32 v5, 31, v4
	v_lshlrev_b64 v[4:5], 11, v[4:5]
	v_lshl_add_u64 v[4:5], s[90:91], 0, v[4:5]
	v_lshl_add_u64 v[4:5], s[8:9], 1, v[4:5]
	v_lshlrev_b32_e32 v6, 1, v7
	v_mov_b32_e32 v7, v112
	v_lshl_add_u64 v[4:5], v[4:5], 0, v[6:7]
	global_store_dwordx4 v[4:5], v[0:3], off
	s_barrier
	s_load_dword s1, s[68:69], 0x10
	s_waitcnt lgkmcnt(0)
	s_lshr_b32 s1, s1, 16
	s_cmp_lg_u32 s1, 0
	s_cselect_b64 s[4:5], -1, 0
	s_cmp_lg_u64 s[4:5], 0
	v_cndmask_b32_e64 v0, 0, 1, s[4:5]
	s_addc_u32 s0, s0, s88
	v_readfirstlane_b32 s1, v0
	s_cmpk_lt_i32 s0, 0x600
	s_cbranch_scc1 .LBB0_317

.LBB0_322:
	s_ashr_i32 s4, s0, 31
	s_lshr_b32 s4, s4, 28
	s_add_i32 s4, s0, s4
	s_ashr_i32 s4, s4, 4
	s_lshl_b32 s10, s4, 6
	s_lshl_b32 s4, s4, 10
	s_sub_i32 s14, s1, s4
	v_mov_b32_e32 v10, v192
	s_ashr_i32 s15, s14, 31
	s_lshl_b64 s[14:15], s[14:15], 2
	v_ashrrev_i32_e32 v11, 4, v10
	s_add_u32 s14, s18, s14
	v_lshlrev_b32_e32 v0, 4, v10
	v_add_u32_e32 v8, s10, v11
	s_addc_u32 s15, s19, s15
	v_and_b32_e32 v4, 0xf0, v0
	v_mov_b32_e32 v5, v112
	v_ashrrev_i32_e32 v9, 31, v8
	v_lshl_add_u64 v[6:7], s[14:15], 0, v[4:5]
	v_lshlrev_b64 v[0:1], 12, v[8:9]
	v_lshl_add_u64 v[0:1], v[6:7], 0, v[0:1]
	global_load_dwordx4 v[0:3], v[0:1], off
	v_add_u32_e32 v12, 32, v8
	v_ashrrev_i32_e32 v13, 31, v12
	v_lshlrev_b64 v[12:13], 12, v[12:13]
	v_lshl_add_u64 v[12:13], v[6:7], 0, v[12:13]
	global_load_dwordx4 v[14:17], v[12:13], off
	v_mul_lo_u32 v5, v11, s3
	v_add3_u32 v4, 0, v4, v5
	v_add_u32_e32 v5, 0x2080, v4
	s_ashr_i32 s11, s10, 31
	s_add_i32 s0, s0, s88
	s_waitcnt vmcnt(1)
	ds_write2_b32 v4, v0, v1 offset1:1
	ds_write2_b32 v4, v2, v3 offset0:2 offset1:3
	v_ashrrev_i32_e32 v6, 3, v10
	s_waitcnt vmcnt(0)
	ds_write2_b32 v5, v14, v15 offset1:1
	v_add_u32_e32 v0, 0x2088, v4
	ds_write2_b32 v0, v16, v17 offset1:1
	v_lshlrev_b32_e32 v0, 3, v10
	v_and_b32_e32 v7, 56, v0
	v_mul_u32_u24_e32 v0, 0x104, v7
	v_lshlrev_b32_e32 v1, 2, v6
	v_add3_u32 v4, 0, v0, v1
	s_waitcnt lgkmcnt(0)
	s_barrier
	ds_read2_b32 v[0:1], v4 offset1:65
	ds_read2_b32 v[2:3], v4 offset0:130 offset1:195
	v_add_u32_e32 v4, 0x400, v4
	s_waitcnt lgkmcnt(1)
	v_cvt_pk_bf16_f32 v0, v0, v1
	s_waitcnt lgkmcnt(0)
	v_cvt_pk_bf16_f32 v1, v2, v3
	ds_read2_b32 v[2:3], v4 offset0:4 offset1:69
	ds_read2_b32 v[4:5], v4 offset0:134 offset1:199
	s_waitcnt lgkmcnt(1)
	v_cvt_pk_bf16_f32 v2, v2, v3
	s_waitcnt lgkmcnt(0)
	v_cvt_pk_bf16_f32 v3, v4, v5
	v_subrev_u32_e32 v4, s4, v6
	v_add_u32_e32 v4, s1, v4
	v_ashrrev_i32_e32 v5, 31, v4
	v_lshlrev_b64 v[4:5], 12, v[4:5]
	v_lshl_add_u64 v[4:5], s[8:9], 0, v[4:5]
	v_lshl_add_u64 v[4:5], s[10:11], 1, v[4:5]
	v_lshlrev_b32_e32 v6, 1, v7
	v_mov_b32_e32 v7, v112
	s_add_i32 s1, s1, s5
	v_lshl_add_u64 v[4:5], v[4:5], 0, v[6:7]
	s_cmpk_gt_i32 s0, 0x1ff
	global_store_dwordx4 v[4:5], v[0:3], off
	s_barrier
	s_cbranch_scc0 .LBB0_322

.LBB0_330:
	s_mul_hi_i32 s1, s0, 0x2aaaaaab
	s_lshr_b32 s4, s1, 31
	s_ashr_i32 s1, s1, 3
	s_add_i32 s1, s1, s4
	s_mul_i32 s4, s1, 48
	s_sub_i32 s4, s0, s4
	s_lshl_b32 s14, s4, 6
	s_ashr_i32 s15, s14, 31
	v_mov_b32_e32 v8, v192
	s_lshl_b32 s10, s1, 6
	s_lshl_b64 s[4:5], s[14:15], 2
	s_add_u32 s4, s44, s4
	v_lshlrev_b32_e32 v0, 4, v8
	v_ashrrev_i32_e32 v9, 4, v8
	s_addc_u32 s5, s45, s5
	v_and_b32_e32 v4, 0xf0, v0
	v_mov_b32_e32 v5, v112
	v_lshl_add_u64 v[6:7], s[4:5], 0, v[4:5]
	v_add_u32_e32 v5, s10, v9
	v_mad_i64_i32 v[0:1], s[4:5], v5, s17, v[6:7]
	global_load_dwordx4 v[0:3], v[0:1], off
	v_add_u32_e32 v12, 32, v5
	v_mad_i64_i32 v[12:13], s[4:5], v12, s17, v[6:7]
	global_load_dwordx4 v[14:17], v[12:13], off
	v_mul_lo_u32 v9, v9, s16
	v_add3_u32 v4, 0, v4, v9
	s_ashr_i32 s11, s10, 31
	s_waitcnt vmcnt(1)
	ds_write2_b32 v4, v0, v1 offset1:1
	ds_write2_b32 v4, v2, v3 offset0:2 offset1:3
	v_add_u32_e32 v5, 0x2080, v4
	v_ashrrev_i32_e32 v6, 3, v8
	s_waitcnt vmcnt(0)
	ds_write2_b32 v5, v14, v15 offset1:1
	v_add_u32_e32 v0, 0x2088, v4
	ds_write2_b32 v0, v16, v17 offset1:1
	v_lshlrev_b32_e32 v0, 3, v8
	v_and_b32_e32 v7, 56, v0
	v_mul_u32_u24_e32 v0, 0x104, v7
	v_lshlrev_b32_e32 v1, 2, v6
	v_add3_u32 v4, 0, v0, v1
	s_waitcnt lgkmcnt(0)
	s_barrier
	ds_read2_b32 v[0:1], v4 offset1:65
	ds_read2_b32 v[2:3], v4 offset0:130 offset1:195
	v_add_u32_e32 v4, 0x400, v4
	s_waitcnt lgkmcnt(1)
	v_cvt_pk_bf16_f32 v0, v0, v1
	s_waitcnt lgkmcnt(0)
	v_cvt_pk_bf16_f32 v1, v2, v3
	ds_read2_b32 v[2:3], v4 offset0:4 offset1:69
	ds_read2_b32 v[4:5], v4 offset0:134 offset1:199
	s_waitcnt lgkmcnt(1)
	v_cvt_pk_bf16_f32 v2, v2, v3
	s_waitcnt lgkmcnt(0)
	v_cvt_pk_bf16_f32 v3, v4, v5
	v_add_u32_e32 v4, s14, v6
	v_ashrrev_i32_e32 v5, 31, v4
	v_lshlrev_b64 v[4:5], 11, v[4:5]
	v_lshl_add_u64 v[4:5], s[90:91], 0, v[4:5]
	v_lshl_add_u64 v[4:5], s[10:11], 1, v[4:5]
	v_lshlrev_b32_e32 v6, 1, v7
	v_mov_b32_e32 v7, v112
	v_lshl_add_u64 v[4:5], v[4:5], 0, v[6:7]
	global_store_dwordx4 v[4:5], v[0:3], off
	s_barrier
	s_load_dword s1, s[68:69], 0x10
	s_waitcnt lgkmcnt(0)
	s_lshr_b32 s1, s1, 16
	s_cmp_lg_u32 s1, 0
	s_cselect_b64 s[4:5], -1, 0
	s_cmp_lg_u64 s[4:5], 0
	v_cndmask_b32_e64 v0, 0, 1, s[4:5]
	s_addc_u32 s0, s0, s88
	v_readfirstlane_b32 s1, v0
	s_cmpk_lt_i32 s0, 0x300
	s_cbranch_scc1 .LBB0_330

.LBB0_335:
	s_ashr_i32 s4, s0, 31
	s_lshr_b32 s4, s4, 28
	s_add_i32 s4, s0, s4
	s_ashr_i32 s4, s4, 4
	s_lshl_b32 s14, s4, 6
	s_lshl_b32 s4, s4, 10
	s_sub_i32 s16, s1, s4
	v_mov_b32_e32 v10, v192
	s_ashr_i32 s17, s16, 31
	s_lshl_b64 s[16:17], s[16:17], 2
	v_ashrrev_i32_e32 v11, 4, v10
	s_add_u32 s16, s50, s16
	v_lshlrev_b32_e32 v0, 4, v10
	v_add_u32_e32 v8, s14, v11
	s_addc_u32 s17, s51, s17
	v_and_b32_e32 v4, 0xf0, v0
	v_mov_b32_e32 v5, v112
	v_ashrrev_i32_e32 v9, 31, v8
	v_lshl_add_u64 v[6:7], s[16:17], 0, v[4:5]
	v_lshlrev_b64 v[0:1], 12, v[8:9]
	v_lshl_add_u64 v[0:1], v[6:7], 0, v[0:1]
	global_load_dwordx4 v[0:3], v[0:1], off
	v_add_u32_e32 v12, 32, v8
	v_ashrrev_i32_e32 v13, 31, v12
	v_lshlrev_b64 v[12:13], 12, v[12:13]
	v_lshl_add_u64 v[12:13], v[6:7], 0, v[12:13]
	global_load_dwordx4 v[14:17], v[12:13], off
	v_mul_lo_u32 v5, v11, s18
	v_add3_u32 v4, 0, v4, v5
	v_add_u32_e32 v5, 0x2080, v4
	s_ashr_i32 s15, s14, 31
	s_add_i32 s0, s0, s88
	s_waitcnt vmcnt(1)
	ds_write2_b32 v4, v0, v1 offset1:1
	ds_write2_b32 v4, v2, v3 offset0:2 offset1:3
	v_ashrrev_i32_e32 v6, 3, v10
	s_waitcnt vmcnt(0)
	ds_write2_b32 v5, v14, v15 offset1:1
	v_add_u32_e32 v0, 0x2088, v4
	ds_write2_b32 v0, v16, v17 offset1:1
	v_lshlrev_b32_e32 v0, 3, v10
	v_and_b32_e32 v7, 56, v0
	v_mul_u32_u24_e32 v0, 0x104, v7
	v_lshlrev_b32_e32 v1, 2, v6
	v_add3_u32 v4, 0, v0, v1
	s_waitcnt lgkmcnt(0)
	s_barrier
	ds_read2_b32 v[0:1], v4 offset1:65
	ds_read2_b32 v[2:3], v4 offset0:130 offset1:195
	v_add_u32_e32 v4, 0x400, v4
	s_waitcnt lgkmcnt(1)
	v_cvt_pk_bf16_f32 v0, v0, v1
	s_waitcnt lgkmcnt(0)
	v_cvt_pk_bf16_f32 v1, v2, v3
	ds_read2_b32 v[2:3], v4 offset0:4 offset1:69
	ds_read2_b32 v[4:5], v4 offset0:134 offset1:199
	s_waitcnt lgkmcnt(1)
	v_cvt_pk_bf16_f32 v2, v2, v3
	s_waitcnt lgkmcnt(0)
	v_cvt_pk_bf16_f32 v3, v4, v5
	v_subrev_u32_e32 v4, s4, v6
	v_add_u32_e32 v4, s1, v4
	v_ashrrev_i32_e32 v5, 31, v4
	v_lshlrev_b64 v[4:5], 11, v[4:5]
	v_lshl_add_u64 v[4:5], s[10:11], 0, v[4:5]
	v_lshl_add_u64 v[4:5], s[14:15], 1, v[4:5]
	v_lshlrev_b32_e32 v6, 1, v7
	v_mov_b32_e32 v7, v112
	s_add_i32 s1, s1, s5
	v_lshl_add_u64 v[4:5], v[4:5], 0, v[6:7]
	s_cmpk_gt_i32 s0, 0xff
	global_store_dwordx4 v[4:5], v[0:3], off
	s_barrier
	s_cbranch_scc0 .LBB0_335

.LBB0_342:
	s_mul_hi_i32 s1, s0, 0x2aaaaaab
	s_lshr_b32 s4, s1, 31
	s_ashr_i32 s1, s1, 3
	s_add_i32 s1, s1, s4
	s_mul_i32 s4, s1, 48
	s_sub_i32 s4, s0, s4
	s_lshl_b32 s8, s4, 6
	s_ashr_i32 s9, s8, 31
	v_mov_b32_e32 v8, v192
	s_lshl_b32 s6, s1, 6
	s_lshl_b64 s[4:5], s[8:9], 2
	s_add_u32 s4, s20, s4
	v_lshlrev_b32_e32 v0, 4, v8
	v_ashrrev_i32_e32 v9, 4, v8
	s_addc_u32 s5, s21, s5
	v_and_b32_e32 v4, 0xf0, v0
	v_mov_b32_e32 v5, v112
	v_lshl_add_u64 v[6:7], s[4:5], 0, v[4:5]
	v_add_u32_e32 v5, s6, v9
	v_mad_i64_i32 v[0:1], s[4:5], v5, s11, v[6:7]
	global_load_dwordx4 v[0:3], v[0:1], off
	v_add_u32_e32 v12, 32, v5
	v_mad_i64_i32 v[12:13], s[4:5], v12, s11, v[6:7]
	global_load_dwordx4 v[14:17], v[12:13], off
	v_mul_lo_u32 v9, v9, s10
	v_add3_u32 v4, 0, v4, v9
	s_ashr_i32 s7, s6, 31
	s_waitcnt vmcnt(1)
	ds_write2_b32 v4, v0, v1 offset1:1
	ds_write2_b32 v4, v2, v3 offset0:2 offset1:3
	v_add_u32_e32 v5, 0x2080, v4
	v_ashrrev_i32_e32 v6, 3, v8
	s_waitcnt vmcnt(0)
	ds_write2_b32 v5, v14, v15 offset1:1
	v_add_u32_e32 v0, 0x2088, v4
	ds_write2_b32 v0, v16, v17 offset1:1
	v_lshlrev_b32_e32 v0, 3, v8
	v_and_b32_e32 v7, 56, v0
	v_mul_u32_u24_e32 v0, 0x104, v7
	v_lshlrev_b32_e32 v1, 2, v6
	v_add3_u32 v4, 0, v0, v1
	s_waitcnt lgkmcnt(0)
	s_barrier
	ds_read2_b32 v[0:1], v4 offset1:65
	ds_read2_b32 v[2:3], v4 offset0:130 offset1:195
	v_add_u32_e32 v4, 0x400, v4
	s_waitcnt lgkmcnt(1)
	v_cvt_pk_bf16_f32 v0, v0, v1
	s_waitcnt lgkmcnt(0)
	v_cvt_pk_bf16_f32 v1, v2, v3
	ds_read2_b32 v[2:3], v4 offset0:4 offset1:69
	ds_read2_b32 v[4:5], v4 offset0:134 offset1:199
	s_waitcnt lgkmcnt(1)
	v_cvt_pk_bf16_f32 v2, v2, v3
	s_waitcnt lgkmcnt(0)
	v_cvt_pk_bf16_f32 v3, v4, v5
	v_add_u32_e32 v4, s8, v6
	v_ashrrev_i32_e32 v5, 31, v4
	v_lshlrev_b64 v[4:5], 11, v[4:5]
	v_lshl_add_u64 v[4:5], s[90:91], 0, v[4:5]
	v_lshl_add_u64 v[4:5], s[6:7], 1, v[4:5]
	v_lshlrev_b32_e32 v6, 1, v7
	v_mov_b32_e32 v7, v112
	v_lshl_add_u64 v[4:5], v[4:5], 0, v[6:7]
	global_store_dwordx4 v[4:5], v[0:3], off
	s_barrier
	s_load_dword s1, s[68:69], 0x10
	s_waitcnt lgkmcnt(0)
	s_lshr_b32 s1, s1, 16
	s_cmp_lg_u32 s1, 0
	s_cselect_b64 s[4:5], -1, 0
	s_cmp_lg_u64 s[4:5], 0
	v_cndmask_b32_e64 v0, 0, 1, s[4:5]
	s_addc_u32 s0, s0, s88
	v_readfirstlane_b32 s1, v0
	s_cmpk_lt_i32 s0, 0x300
	s_cbranch_scc1 .LBB0_342

.LBB0_347:
	s_ashr_i32 s4, s0, 31
	s_lshr_b32 s4, s4, 28
	s_add_i32 s4, s0, s4
	s_ashr_i32 s4, s4, 4
	s_lshl_b32 s8, s4, 6
	s_lshl_b32 s4, s4, 10
	s_sub_i32 s10, s1, s4
	v_mov_b32_e32 v10, v192
	s_ashr_i32 s11, s10, 31
	s_lshl_b64 s[10:11], s[10:11], 2
	v_ashrrev_i32_e32 v11, 4, v10
	s_add_u32 s10, s24, s10
	v_lshlrev_b32_e32 v0, 4, v10
	v_add_u32_e32 v8, s8, v11
	s_addc_u32 s11, s25, s11
	v_and_b32_e32 v4, 0xf0, v0
	v_mov_b32_e32 v5, v112
	v_ashrrev_i32_e32 v9, 31, v8
	v_lshl_add_u64 v[6:7], s[10:11], 0, v[4:5]
	v_lshlrev_b64 v[0:1], 12, v[8:9]
	v_lshl_add_u64 v[0:1], v[6:7], 0, v[0:1]
	global_load_dwordx4 v[0:3], v[0:1], off
	v_add_u32_e32 v12, 32, v8
	v_ashrrev_i32_e32 v13, 31, v12
	v_lshlrev_b64 v[12:13], 12, v[12:13]
	v_lshl_add_u64 v[12:13], v[6:7], 0, v[12:13]
	global_load_dwordx4 v[14:17], v[12:13], off
	v_mul_lo_u32 v5, v11, s14
	v_add3_u32 v4, 0, v4, v5
	v_add_u32_e32 v5, 0x2080, v4
	s_ashr_i32 s9, s8, 31
	s_add_i32 s0, s0, s88
	s_waitcnt vmcnt(1)
	ds_write2_b32 v4, v0, v1 offset1:1
	ds_write2_b32 v4, v2, v3 offset0:2 offset1:3
	v_ashrrev_i32_e32 v6, 3, v10
	s_waitcnt vmcnt(0)
	ds_write2_b32 v5, v14, v15 offset1:1
	v_add_u32_e32 v0, 0x2088, v4
	ds_write2_b32 v0, v16, v17 offset1:1
	v_lshlrev_b32_e32 v0, 3, v10
	v_and_b32_e32 v7, 56, v0
	v_mul_u32_u24_e32 v0, 0x104, v7
	v_lshlrev_b32_e32 v1, 2, v6
	v_add3_u32 v4, 0, v0, v1
	s_waitcnt lgkmcnt(0)
	s_barrier
	ds_read2_b32 v[0:1], v4 offset1:65
	ds_read2_b32 v[2:3], v4 offset0:130 offset1:195
	v_add_u32_e32 v4, 0x400, v4
	s_waitcnt lgkmcnt(1)
	v_cvt_pk_bf16_f32 v0, v0, v1
	s_waitcnt lgkmcnt(0)
	v_cvt_pk_bf16_f32 v1, v2, v3
	ds_read2_b32 v[2:3], v4 offset0:4 offset1:69
	ds_read2_b32 v[4:5], v4 offset0:134 offset1:199
	s_waitcnt lgkmcnt(1)
	v_cvt_pk_bf16_f32 v2, v2, v3
	s_waitcnt lgkmcnt(0)
	v_cvt_pk_bf16_f32 v3, v4, v5
	v_subrev_u32_e32 v4, s4, v6
	v_add_u32_e32 v4, s1, v4
	v_ashrrev_i32_e32 v5, 31, v4
	v_lshlrev_b64 v[4:5], 11, v[4:5]
	v_lshl_add_u64 v[4:5], s[6:7], 0, v[4:5]
	v_lshl_add_u64 v[4:5], s[8:9], 1, v[4:5]
	v_lshlrev_b32_e32 v6, 1, v7
	v_mov_b32_e32 v7, v112
	s_add_i32 s1, s1, s5
	v_lshl_add_u64 v[4:5], v[4:5], 0, v[6:7]
	s_cmpk_gt_i32 s0, 0xff
	global_store_dwordx4 v[4:5], v[0:3], off
	s_barrier
	s_cbranch_scc0 .LBB0_347

.LBB0_352:
	s_mul_hi_i32 s1, s0, 0x2aaaaaab
	s_lshr_b32 s4, s1, 31
	s_ashr_i32 s1, s1, 2
	s_add_i32 s1, s1, s4
	s_mul_i32 s4, s1, 24
	s_sub_i32 s4, s0, s4
	s_lshl_b32 s8, s4, 6
	s_ashr_i32 s9, s8, 31
	v_mov_b32_e32 v8, v192
	s_lshl_b32 s6, s1, 6
	s_lshl_b64 s[4:5], s[8:9], 2
	s_add_u32 s4, s28, s4
	v_lshlrev_b32_e32 v0, 4, v8
	v_ashrrev_i32_e32 v9, 4, v8
	s_addc_u32 s5, s29, s5
	v_and_b32_e32 v4, 0xf0, v0
	v_mov_b32_e32 v5, v112
	v_lshl_add_u64 v[6:7], s[4:5], 0, v[4:5]
	v_add_u32_e32 v5, s6, v9
	v_mad_i64_i32 v[0:1], s[4:5], v5, s10, v[6:7]
	global_load_dwordx4 v[0:3], v[0:1], off
	v_add_u32_e32 v12, 32, v5
	v_mad_i64_i32 v[12:13], s[4:5], v12, s10, v[6:7]
	global_load_dwordx4 v[14:17], v[12:13], off
	v_mul_lo_u32 v9, v9, s11
	v_add3_u32 v4, 0, v4, v9
	s_ashr_i32 s7, s6, 31
	s_waitcnt vmcnt(1)
	ds_write2_b32 v4, v0, v1 offset1:1
	ds_write2_b32 v4, v2, v3 offset0:2 offset1:3
	v_add_u32_e32 v5, 0x2080, v4
	v_ashrrev_i32_e32 v6, 3, v8
	s_waitcnt vmcnt(0)
	ds_write2_b32 v5, v14, v15 offset1:1
	v_add_u32_e32 v0, 0x2088, v4
	ds_write2_b32 v0, v16, v17 offset1:1
	v_lshlrev_b32_e32 v0, 3, v8
	v_and_b32_e32 v7, 56, v0
	v_mul_u32_u24_e32 v0, 0x104, v7
	v_lshlrev_b32_e32 v1, 2, v6
	v_add3_u32 v4, 0, v0, v1
	s_waitcnt lgkmcnt(0)
	s_barrier
	ds_read2_b32 v[0:1], v4 offset1:65
	ds_read2_b32 v[2:3], v4 offset0:130 offset1:195
	v_add_u32_e32 v4, 0x400, v4
	s_waitcnt lgkmcnt(1)
	v_cvt_pk_bf16_f32 v0, v0, v1
	s_waitcnt lgkmcnt(0)
	v_cvt_pk_bf16_f32 v1, v2, v3
	ds_read2_b32 v[2:3], v4 offset0:4 offset1:69
	ds_read2_b32 v[4:5], v4 offset0:134 offset1:199
	s_waitcnt lgkmcnt(1)
	v_cvt_pk_bf16_f32 v2, v2, v3
	s_waitcnt lgkmcnt(0)
	v_cvt_pk_bf16_f32 v3, v4, v5
	v_add_u32_e32 v4, s8, v6
	v_ashrrev_i32_e32 v5, 31, v4
	v_lshlrev_b64 v[4:5], 11, v[4:5]
	v_lshl_add_u64 v[4:5], s[90:91], 0, v[4:5]
	v_lshl_add_u64 v[4:5], s[6:7], 1, v[4:5]
	v_lshlrev_b32_e32 v6, 1, v7
	v_mov_b32_e32 v7, v112
	v_lshl_add_u64 v[4:5], v[4:5], 0, v[6:7]
	global_store_dwordx4 v[4:5], v[0:3], off
	s_barrier
	s_load_dword s1, s[68:69], 0x10
	s_waitcnt lgkmcnt(0)
	s_lshr_b32 s1, s1, 16
	s_cmp_lg_u32 s1, 0
	s_cselect_b64 s[4:5], -1, 0
	s_cmp_lg_u64 s[4:5], 0
	v_cndmask_b32_e64 v0, 0, 1, s[4:5]
	s_addc_u32 s0, s0, s88
	v_readfirstlane_b32 s1, v0
	s_cmpk_lt_i32 s0, 0x180
	s_cbranch_scc1 .LBB0_352

.LBB0_357:
	s_ashr_i32 s4, s0, 31
	s_lshr_b32 s4, s4, 28
	s_add_i32 s4, s0, s4
	s_ashr_i32 s4, s4, 4
	s_lshl_b32 s8, s4, 6
	s_lshl_b32 s4, s4, 10
	s_sub_i32 s10, s1, s4
	v_mov_b32_e32 v10, v192
	s_ashr_i32 s11, s10, 31
	s_lshl_b64 s[10:11], s[10:11], 2
	v_ashrrev_i32_e32 v11, 4, v10
	s_add_u32 s10, s42, s10
	v_lshlrev_b32_e32 v0, 4, v10
	v_add_u32_e32 v8, s8, v11
	s_addc_u32 s11, s43, s11
	v_and_b32_e32 v4, 0xf0, v0
	v_mov_b32_e32 v5, v112
	v_ashrrev_i32_e32 v9, 31, v8
	v_lshl_add_u64 v[6:7], s[10:11], 0, v[4:5]
	v_lshlrev_b64 v[0:1], 12, v[8:9]
	v_lshl_add_u64 v[0:1], v[6:7], 0, v[0:1]
	global_load_dwordx4 v[0:3], v[0:1], off
	v_add_u32_e32 v12, 32, v8
	v_ashrrev_i32_e32 v13, 31, v12
	v_lshlrev_b64 v[12:13], 12, v[12:13]
	v_lshl_add_u64 v[12:13], v[6:7], 0, v[12:13]
	global_load_dwordx4 v[14:17], v[12:13], off
	v_mul_lo_u32 v5, v11, s5
	v_add3_u32 v4, 0, v4, v5
	v_add_u32_e32 v5, 0x2080, v4
	s_ashr_i32 s9, s8, 31
	s_add_i32 s0, s0, s88
	s_waitcnt vmcnt(1)
	ds_write2_b32 v4, v0, v1 offset1:1
	ds_write2_b32 v4, v2, v3 offset0:2 offset1:3
	v_ashrrev_i32_e32 v6, 3, v10
	s_waitcnt vmcnt(0)
	ds_write2_b32 v5, v14, v15 offset1:1
	v_add_u32_e32 v0, 0x2088, v4
	ds_write2_b32 v0, v16, v17 offset1:1
	v_lshlrev_b32_e32 v0, 3, v10
	v_and_b32_e32 v7, 56, v0
	v_mul_u32_u24_e32 v0, 0x104, v7
	v_lshlrev_b32_e32 v1, 2, v6
	v_add3_u32 v4, 0, v0, v1
	s_waitcnt lgkmcnt(0)
	s_barrier
	ds_read2_b32 v[0:1], v4 offset1:65
	ds_read2_b32 v[2:3], v4 offset0:130 offset1:195
	v_add_u32_e32 v4, 0x400, v4
	s_waitcnt lgkmcnt(1)
	v_cvt_pk_bf16_f32 v0, v0, v1
	s_waitcnt lgkmcnt(0)
	v_cvt_pk_bf16_f32 v1, v2, v3
	ds_read2_b32 v[2:3], v4 offset0:4 offset1:69
	ds_read2_b32 v[4:5], v4 offset0:134 offset1:199
	s_waitcnt lgkmcnt(1)
	v_cvt_pk_bf16_f32 v2, v2, v3
	s_waitcnt lgkmcnt(0)
	v_cvt_pk_bf16_f32 v3, v4, v5
	v_subrev_u32_e32 v4, s4, v6
	v_add_u32_e32 v4, s1, v4
	v_ashrrev_i32_e32 v5, 31, v4
	v_lshlrev_b64 v[4:5], 11, v[4:5]
	v_lshl_add_u64 v[4:5], s[6:7], 0, v[4:5]
	v_readlane_b32 s4, v252, 54
	v_lshl_add_u64 v[4:5], s[8:9], 1, v[4:5]
	v_lshlrev_b32_e32 v6, 1, v7
	v_mov_b32_e32 v7, v112
	s_add_i32 s1, s1, s4
	v_lshl_add_u64 v[4:5], v[4:5], 0, v[6:7]
	s_cmpk_gt_i32 s0, 0xff
	global_store_dwordx4 v[4:5], v[0:3], off
	s_barrier
	s_cbranch_scc0 .LBB0_357

.LBB0_924:
	s_ashr_i32 s6, s5, 5
	s_ashr_i32 s7, s6, 31
	s_ashr_i32 s8, s5, 8
	s_lshl_b64 s[10:11], s[6:7], 19
	s_add_u32 s10, s56, s10
	s_addc_u32 s11, s57, s11
	s_ashr_i32 s9, s8, 31
	s_lshl_b32 s6, s6, 9
	s_lshl_b64 s[8:9], s[8:9], 11
	s_and_b32 s6, s6, 0x600
	s_or_b32 s6, s8, s6
	s_mul_i32 s7, s9, 0x2400
	s_mul_hi_u32 s8, s6, 0x2400
	s_add_i32 s8, s8, s7
	s_mulk_i32 s6, 0x2400
	s_add_u32 s6, s18, s6
	s_addc_u32 s7, s19, s8
	s_and_b32 s8, s0, 0x100
	s_lshl_b32 s8, s8, 1
	s_add_u32 s6, s6, s8
	s_addc_u32 s7, s7, 0
	s_add_u32 s6, s6, 0x2000
	s_addc_u32 s7, s7, 0
	v_mov_b32_e32 v10, v192
	s_and_b32 s9, s4, 0x1c0
	s_and_b32 s8, s1, 0xc0
	v_ashrrev_i32_e32 v11, 4, v10
	s_lshl_b32 s12, s9, 2
	s_add_u32 s10, s10, s12
	v_lshlrev_b32_e32 v0, 4, v10
	v_add_u32_e32 v8, s8, v11
	s_addc_u32 s11, s11, 0
	v_and_b32_e32 v4, 0xf0, v0
	v_mov_b32_e32 v5, v112
	v_ashrrev_i32_e32 v9, 31, v8
	v_lshl_add_u64 v[6:7], s[10:11], 0, v[4:5]
	v_lshlrev_b64 v[0:1], 11, v[8:9]
	v_lshl_add_u64 v[0:1], v[6:7], 0, v[0:1]
	global_load_dwordx4 v[0:3], v[0:1], off
	v_add_u32_e32 v12, 32, v8
	v_ashrrev_i32_e32 v13, 31, v12
	v_lshlrev_b64 v[12:13], 11, v[12:13]
	v_lshl_add_u64 v[12:13], v[6:7], 0, v[12:13]
	global_load_dwordx4 v[14:17], v[12:13], off
	v_mul_lo_u32 v5, v11, s16
	v_add3_u32 v4, 0, v4, v5
	v_add_u32_e32 v5, 0x2080, v4
	s_add_i32 s5, s5, s88
	s_add_i32 s4, s4, s13
	s_add_i32 s1, s1, s14
	s_add_i32 s0, s0, s15
	s_waitcnt vmcnt(1)
	ds_write2_b32 v4, v0, v1 offset1:1
	ds_write2_b32 v4, v2, v3 offset0:2 offset1:3
	v_ashrrev_i32_e32 v6, 3, v10
	v_and_b32_e32 v7, 1, v10
	v_cmp_eq_u32_e32 vcc, 0, v7
	s_waitcnt vmcnt(0)
	ds_write2_b32 v5, v14, v15 offset1:1
	v_add_u32_e32 v0, 0x2088, v4
	ds_write2_b32 v0, v16, v17 offset1:1
	v_lshlrev_b32_e32 v0, 3, v10
	v_and_b32_e32 v8, 56, v0
	v_mul_u32_u24_e32 v0, 0x104, v8
	v_lshlrev_b32_e32 v1, 2, v6
	v_add3_u32 v4, 0, v0, v1
	s_waitcnt lgkmcnt(0)
	s_barrier
	ds_read2_b32 v[0:1], v4 offset1:65
	ds_read2_b32 v[2:3], v4 offset0:130 offset1:195
	v_add_u32_e32 v4, 0x400, v4
	v_add_u32_e32 v6, s9, v6
	v_or_b32_e32 v9, 4, v8
	s_waitcnt lgkmcnt(1)
	v_cvt_pk_bf16_f32 v0, v0, v1
	s_waitcnt lgkmcnt(0)
	v_cvt_pk_bf16_f32 v1, v2, v3
	ds_read2_b32 v[2:3], v4 offset0:4 offset1:69
	ds_read2_b32 v[4:5], v4 offset0:134 offset1:199
	s_waitcnt lgkmcnt(1)
	v_cvt_pk_bf16_f32 v2, v2, v3
	s_waitcnt lgkmcnt(0)
	v_cvt_pk_bf16_f32 v3, v4, v5
	v_mov_b64_e32 v[4:5], s[6:7]
	v_mad_i64_i32 v[4:5], s[6:7], v6, s74, v[4:5]
	v_add_u32_e32 v6, -4, v8
	s_lshl_b32 s6, s8, 1
	s_mov_b32 s7, s96
	v_cndmask_b32_e32 v6, v6, v8, vcc
	v_lshl_add_u64 v[4:5], v[4:5], 0, s[6:7]
	v_ashrrev_i32_e32 v7, 31, v6
	v_lshl_add_u64 v[6:7], v[6:7], 1, v[4:5]
	global_store_dwordx2 v[6:7], v[0:1], off
	v_add_u32_e32 v0, 8, v8
	v_cndmask_b32_e32 v0, v9, v0, vcc
	v_lshlrev_b32_e32 v0, 1, v0
	v_mov_b32_e32 v1, v112
	v_lshl_add_u64 v[0:1], v[4:5], 0, v[0:1]
	s_cmpk_gt_i32 s5, 0x1ff
	global_store_dwordx2 v[0:1], v[2:3], off
	s_barrier
	s_cbranch_scc0 .LBB0_924

.LBB0_1048:
	s_mul_hi_i32 s6, s0, 0x2e8ba2e9
	s_lshr_b32 s7, s6, 31
	s_ashr_i32 s6, s6, 4
	s_add_i32 s7, s6, s7
	s_mul_i32 s8, s7, 0xffffea00
	s_add_i32 s8, s5, s8
	s_ashr_i32 s9, s8, 31
	s_waitcnt vmcnt(0)
	v_mov_b32_e32 v8, v192
	s_lshl_b32 s6, s7, 6
	s_lshl_b64 s[8:9], s[8:9], 2
	s_add_u32 s8, s1, s8
	v_lshlrev_b32_e32 v0, 4, v8
	v_ashrrev_i32_e32 v9, 4, v8
	s_addc_u32 s9, s4, s9
	v_and_b32_e32 v4, 0xf0, v0
	v_mov_b32_e32 v5, v112
	v_lshl_add_u64 v[6:7], s[8:9], 0, v[4:5]
	v_add_u32_e32 v5, s6, v9
	v_mad_i64_i32 v[0:1], s[8:9], v5, s11, v[6:7]
	global_load_dwordx4 v[0:3], v[0:1], off
	v_add_u32_e32 v12, 32, v5
	v_mad_i64_i32 v[12:13], s[8:9], v12, s11, v[6:7]
	global_load_dwordx4 v[14:17], v[12:13], off
	v_mul_lo_u32 v9, v9, s12
	v_add3_u32 v4, 0, v4, v9
	s_mulk_i32 s7, 0x1600
	s_add_i32 s0, s0, s88
	s_waitcnt vmcnt(1)
	ds_write2_b32 v4, v0, v1 offset1:1
	ds_write2_b32 v4, v2, v3 offset0:2 offset1:3
	v_add_u32_e32 v5, 0x2080, v4
	v_ashrrev_i32_e32 v6, 3, v8
	s_waitcnt vmcnt(0)
	ds_write2_b32 v5, v14, v15 offset1:1
	v_add_u32_e32 v0, 0x2088, v4
	ds_write2_b32 v0, v16, v17 offset1:1
	v_lshlrev_b32_e32 v0, 3, v8
	v_and_b32_e32 v7, 56, v0
	v_mul_u32_u24_e32 v0, 0x104, v7
	v_lshlrev_b32_e32 v1, 2, v6
	v_add3_u32 v4, 0, v0, v1
	s_waitcnt lgkmcnt(0)
	s_barrier
	ds_read2_b32 v[0:1], v4 offset1:65
	ds_read2_b32 v[2:3], v4 offset0:130 offset1:195
	v_add_u32_e32 v4, 0x400, v4
	s_waitcnt lgkmcnt(1)
	v_cvt_pk_bf16_f32 v0, v0, v1
	s_waitcnt lgkmcnt(0)
	v_cvt_pk_bf16_f32 v1, v2, v3
	ds_read2_b32 v[2:3], v4 offset0:4 offset1:69
	ds_read2_b32 v[4:5], v4 offset0:134 offset1:199
	s_waitcnt lgkmcnt(1)
	v_cvt_pk_bf16_f32 v2, v2, v3
	s_waitcnt lgkmcnt(0)
	v_cvt_pk_bf16_f32 v3, v4, v5
	v_subrev_u32_e32 v4, s7, v6
	v_add_u32_e32 v4, s5, v4
	v_ashrrev_i32_e32 v5, 31, v4
	v_lshlrev_b64 v[4:5], 11, v[4:5]
	v_lshl_add_u64 v[4:5], s[14:15], 0, v[4:5]
	s_ashr_i32 s7, s6, 31
	v_lshl_add_u64 v[4:5], s[6:7], 1, v[4:5]
	v_lshlrev_b32_e32 v6, 1, v7
	v_mov_b32_e32 v7, v112
	s_add_i32 s5, s5, s10
	v_lshl_add_u64 v[4:5], v[4:5], 0, v[6:7]
	s_cmpk_lt_i32 s0, 0x580
	global_store_dwordx4 v[4:5], v[0:3], off
	s_barrier
	s_cbranch_scc1 .LBB0_1048

.LBB0_1053:
	s_ashr_i32 s8, s0, 31
	s_lshr_b32 s8, s8, 28
	s_add_i32 s8, s0, s8
	s_ashr_i32 s9, s8, 4
	s_lshl_b32 s8, s9, 6
	s_lshl_b32 s9, s9, 10
	s_sub_i32 s10, s5, s9
	s_waitcnt vmcnt(0)
	v_mov_b32_e32 v10, v192
	s_ashr_i32 s11, s10, 31
	s_lshl_b64 s[10:11], s[10:11], 2
	v_ashrrev_i32_e32 v11, 4, v10
	s_add_u32 s10, s1, s10
	v_lshlrev_b32_e32 v0, 4, v10
	v_add_u32_e32 v8, s8, v11
	s_addc_u32 s11, s4, s11
	v_and_b32_e32 v4, 0xf0, v0
	v_mov_b32_e32 v5, v112
	v_ashrrev_i32_e32 v9, 31, v8
	v_lshl_add_u64 v[6:7], s[10:11], 0, v[4:5]
	v_lshlrev_b64 v[0:1], 12, v[8:9]
	v_lshl_add_u64 v[0:1], v[6:7], 0, v[0:1]
	global_load_dwordx4 v[0:3], v[0:1], off
	v_add_u32_e32 v12, 32, v8
	v_ashrrev_i32_e32 v13, 31, v12
	v_lshlrev_b64 v[12:13], 12, v[12:13]
	v_lshl_add_u64 v[12:13], v[6:7], 0, v[12:13]
	global_load_dwordx4 v[14:17], v[12:13], off
	v_mul_lo_u32 v5, v11, s13
	v_add3_u32 v4, 0, v4, v5
	v_add_u32_e32 v5, 0x2080, v4
	s_add_i32 s0, s0, s88
	s_waitcnt vmcnt(1)
	ds_write2_b32 v4, v0, v1 offset1:1
	ds_write2_b32 v4, v2, v3 offset0:2 offset1:3
	v_ashrrev_i32_e32 v6, 3, v10
	s_waitcnt vmcnt(0)
	ds_write2_b32 v5, v14, v15 offset1:1
	v_add_u32_e32 v0, 0x2088, v4
	ds_write2_b32 v0, v16, v17 offset1:1
	v_lshlrev_b32_e32 v0, 3, v10
	v_and_b32_e32 v7, 56, v0
	v_mul_u32_u24_e32 v0, 0x104, v7
	v_lshlrev_b32_e32 v1, 2, v6
	v_add3_u32 v4, 0, v0, v1
	s_waitcnt lgkmcnt(0)
	s_barrier
	ds_read2_b32 v[0:1], v4 offset1:65
	ds_read2_b32 v[2:3], v4 offset0:130 offset1:195
	v_add_u32_e32 v4, 0x400, v4
	s_waitcnt lgkmcnt(1)
	v_cvt_pk_bf16_f32 v0, v0, v1
	s_waitcnt lgkmcnt(0)
	v_cvt_pk_bf16_f32 v1, v2, v3
	ds_read2_b32 v[2:3], v4 offset0:4 offset1:69
	ds_read2_b32 v[4:5], v4 offset0:134 offset1:199
	s_waitcnt lgkmcnt(1)
	v_cvt_pk_bf16_f32 v2, v2, v3
	s_waitcnt lgkmcnt(0)
	v_cvt_pk_bf16_f32 v3, v4, v5
	v_subrev_u32_e32 v4, s9, v6
	v_add_u32_e32 v6, s5, v4
	v_mov_b64_e32 v[4:5], s[6:7]
	v_mad_i64_i32 v[4:5], s[10:11], v6, s14, v[4:5]
	s_ashr_i32 s9, s8, 31
	v_lshl_add_u64 v[4:5], s[8:9], 1, v[4:5]
	v_lshlrev_b32_e32 v6, 1, v7
	v_mov_b32_e32 v7, v112
	s_add_i32 s5, s5, s12
	v_lshl_add_u64 v[4:5], v[4:5], 0, v[6:7]
	s_cmpk_gt_i32 s0, 0x2bf
	global_store_dwordx4 v[4:5], v[0:3], off
	s_barrier
	s_cbranch_scc0 .LBB0_1053
